# mixer C epilogue: four 8-byte output stores per lane paired into two 16-byte stores via v_permlane16_swap between the fq rows (store widening)
# baseline (speedup 1.0000x reference)
; #define LAS __attribute__((address_space(3)))
; __device__ __forceinline__ void mixC_mfma(const bf16* P, const float* rpb  , bf16* MIX, LAS unsigned char* lds, int bid, int G, int tid) {
;     ...
;         m1 = fmaxf(m1, __shfl_xor(m1, 16)); m1 = fmaxf(m1, __shfl_xor(m1, 32));
;         float l1 = 0.f;
; #pragma unroll
;         for (int kt = 0; kt < 8; ++kt)
; #pragma unroll
;             for (int t = 0; t < 4; ++t) { const float p = __builtin_amdgcn_exp2f(S[kt][t] - m1); S[kt][t] = p; l1 += p; }
; #pragma unroll
;         for (int kt = 8; kt < 16; ++kt) { f32x4 z = {0.f, 0.f, 0.f, 0.f};
;             z = __builtin_amdgcn_mfma_f32_16x16x32_bf16(Kl[kt - 8][0], Qn0, z, 0, 0, 0);
;             S[kt] = __builtin_amdgcn_mfma_f32_16x16x32_bf16(Kl[kt - 8][1], Qn1, z, 0, 0, 0); }
;         asm volatile("" ::: "memory");
;         if (un + G < NU) c_prefetch(P, un + G, tid, wave, fr, fq, vpre, Qn0, Qn1, Kn);
;         float mx = m1;
; #pragma unroll
;         for (int kt = 8; kt < 16; ++kt)
; #pragma unroll
;             for (int t = 0; t < 4; ++t) {
;                 const bool ok = (unsigned)(d0 + 16 * (kt & 1) + t) < 16u;
;                 const float sv = ok ? S[kt][t] * (0.125f * L2E) + rpl[(kt >> 1) * 31 + 16 * (kt & 1) + t] : -1e30f;
;                 S[kt][t] = sv; mx = fmaxf(mx, sv);
;             }
;         mx = fmaxf(mx, __shfl_xor(mx, 16)); mx = fmaxf(mx, __shfl_xor(mx, 32));
;         const float sc1 = __builtin_amdgcn_exp2f(m1 - mx);
;         float den = l1 * sc1;
; #pragma unroll
;         for (int kt = 0; kt < 8; ++kt) S[kt] = S[kt] * sc1;
; #pragma unroll
;         for (int kt = 8; kt < 16; ++kt)
; #pragma unroll
;             for (int t = 0; t < 4; ++t) { const float p = __builtin_amdgcn_exp2f(S[kt][t] - mx); S[kt][t] = p; den += p; }
;         den += __shfl_xor(den, 16); den += __shfl_xor(den, 32);
;         f32x4 O[4];
; #pragma unroll
;         for (int dt = 0; dt < 4; ++dt) O[dt] = (f32x4){0.f, 0.f, 0.f, 0.f};
;         const LAS unsigned char* vb = Vs + ((rs - R0) * 64 + kcol0 + 4 * fq + (fr >> 2)) * VROW + 8 * (lane & 3);
; #pragma unroll
;         for (int p = 0; p < 8; ++p) {
;             const bf16x8 Pf = pack_p(S[2 * p], S[2 * p + 1]);
.LBB0_352:
	s_or_b64 exec, exec, s[0:1]
	s_waitcnt lgkmcnt(0)
	v_max_f32_e32 v110, v135, v135
	v_max_f32_e32 v111, v134, v134
	v_max_f32_e32 v135, v111, v110
	v_max3_f32 v110, v135, v139, v138
	v_max3_f32 v110, v110, v144, v143
	v_max3_f32 v110, v110, v149, v145
	v_max3_f32 v110, v110, v152, v151
	v_max3_f32 v110, v110, v154, v153
	v_max3_f32 v110, v110, v156, v155
	v_max3_f32 v110, v110, v158, v157
	v_max3_f32 v110, v110, v159, v148
	v_max3_f32 v110, v110, v150, v146
	v_max3_f32 v110, v110, v142, v140
	v_max3_f32 v110, v110, v147, v136
	v_max3_f32 v110, v110, v141, v131
	v_max3_f32 v110, v110, v137, v128
	v_max3_f32 v110, v110, v133, v132
	v_max3_f32 v134, v110, v130, v129
	v_sub_f32_e32 v110, v230, v135
	v_exp_f32_e32 v110, v110
	v_sub_f32_e32 v111, v217, v135
	v_exp_f32_e32 v111, v111
	v_sub_f32_e32 v112, v203, v135
	v_exp_f32_e32 v112, v112
	v_sub_f32_e32 v113, v202, v135
	v_exp_f32_e32 v113, v113
	v_add_f32_e32 v114, 0, v110
	v_add_f32_e32 v114, v111, v114
	v_add_f32_e32 v114, v112, v114
	v_add_f32_e32 v118, v113, v114
	v_sub_f32_e32 v114, v205, v135
	v_exp_f32_e32 v114, v114
	v_sub_f32_e32 v115, v204, v135
	v_exp_f32_e32 v115, v115
	v_sub_f32_e32 v116, v199, v135
	v_exp_f32_e32 v116, v116
	v_sub_f32_e32 v117, v198, v135
	v_exp_f32_e32 v117, v117
	v_add_f32_e32 v118, v114, v118
	v_add_f32_e32 v118, v115, v118
	v_add_f32_e32 v118, v116, v118
	v_add_f32_e32 v122, v117, v118
	v_sub_f32_e32 v118, v201, v135
	v_exp_f32_e32 v118, v118
	v_sub_f32_e32 v119, v200, v135
	v_exp_f32_e32 v119, v119
	v_sub_f32_e32 v120, v195, v135
	v_exp_f32_e32 v120, v120
	v_sub_f32_e32 v121, v194, v135
	v_exp_f32_e32 v121, v121
	v_add_f32_e32 v122, v118, v122
	v_add_f32_e32 v122, v119, v122
	v_add_f32_e32 v122, v120, v122
	v_add_f32_e32 v160, v121, v122
	v_sub_f32_e32 v122, v197, v135
	v_exp_f32_e32 v122, v122
	v_sub_f32_e32 v123, v196, v135
	v_exp_f32_e32 v123, v123
	v_sub_f32_e32 v124, v191, v135
	v_exp_f32_e32 v124, v124
	v_sub_f32_e32 v125, v190, v135
	v_exp_f32_e32 v125, v125
	v_add_f32_e32 v160, v122, v160
	v_add_f32_e32 v160, v123, v160
	v_add_f32_e32 v160, v124, v160
	v_add_f32_e32 v164, v125, v160
	v_sub_f32_e32 v160, v193, v135
	v_exp_f32_e32 v160, v160
	v_sub_f32_e32 v161, v192, v135
	v_exp_f32_e32 v161, v161
	v_sub_f32_e32 v162, v187, v135
	v_exp_f32_e32 v162, v162
	v_sub_f32_e32 v163, v186, v135
	v_exp_f32_e32 v163, v163
	v_add_f32_e32 v164, v160, v164
	v_add_f32_e32 v164, v161, v164
	v_add_f32_e32 v164, v162, v164
	v_add_f32_e32 v168, v163, v164
	v_sub_f32_e32 v164, v189, v135
	v_exp_f32_e32 v164, v164
	v_sub_f32_e32 v165, v188, v135
	v_exp_f32_e32 v165, v165
	v_sub_f32_e32 v166, v183, v135
	v_exp_f32_e32 v166, v166
	v_sub_f32_e32 v167, v182, v135
	v_exp_f32_e32 v167, v167
	v_add_f32_e32 v168, v164, v168
	v_add_f32_e32 v168, v165, v168
	v_add_f32_e32 v168, v166, v168
	v_add_f32_e32 v172, v167, v168
	v_sub_f32_e32 v168, v185, v135
	v_max3_f32 v134, v134, v127, v126
	v_exp_f32_e32 v168, v168
	v_sub_f32_e32 v169, v184, v135
	ds_bpermute_b32 v174, v219, v134
	v_exp_f32_e32 v169, v169
	v_sub_f32_e32 v170, v233, v135
	v_exp_f32_e32 v170, v170
	v_sub_f32_e32 v171, v232, v135
	v_exp_f32_e32 v171, v171
	v_add_f32_e32 v172, v168, v172
	v_add_f32_e32 v172, v169, v172
	s_waitcnt lgkmcnt(0)
	v_max_f32_e32 v174, v174, v174
	v_add_f32_e32 v172, v170, v172
	v_max_f32_e32 v134, v134, v174
	v_add_f32_e32 v176, v171, v172
	v_sub_f32_e32 v172, v235, v135
	ds_bpermute_b32 v177, v220, v134
	v_exp_f32_e32 v172, v172
	v_sub_f32_e32 v175, v237, v135
	v_sub_f32_e32 v173, v234, v135
	v_exp_f32_e32 v174, v175
	v_add_f32_e32 v178, v172, v176
	s_waitcnt lgkmcnt(0)
	v_max_f32_e32 v176, v177, v177
	v_max_f32_e32 v134, v134, v176
	v_sub_f32_e32 v175, v236, v135
	v_sub_f32_e32 v135, v135, v134
	v_exp_f32_e32 v176, v135
	v_exp_f32_e32 v173, v173
	v_exp_f32_e32 v175, v175
	s_sub_i32 s0, s92, s91
	v_pk_mul_f32 v[182:183], v[116:117], v[176:177] op_sel_hi:[1,0]
	v_sub_f32_e32 v116, v139, v134
	v_exp_f32_e32 v194, v116
	v_sub_f32_e32 v116, v138, v134
	v_add_f32_e32 v135, v173, v178
	v_exp_f32_e32 v195, v116
	v_add_f32_e32 v135, v174, v135
	v_add_f32_e32 v135, v175, v135
	v_mov_b32_e32 v138, v194
	v_fmac_f32_e32 v138, v135, v176
	v_add_f32_e32 v135, v195, v138
	v_sub_f32_e32 v138, v144, v134
	v_exp_f32_e32 v196, v138
	v_sub_f32_e32 v138, v143, v134
	v_exp_f32_e32 v197, v138
	v_sub_f32_e32 v138, v149, v134
	v_exp_f32_e32 v198, v138
	v_sub_f32_e32 v138, v145, v134
	v_exp_f32_e32 v199, v138
	v_sub_f32_e32 v138, v152, v134
	v_exp_f32_e32 v200, v138
	v_sub_f32_e32 v138, v151, v134
	v_exp_f32_e32 v201, v138
	v_sub_f32_e32 v138, v154, v134
	v_exp_f32_e32 v202, v138
	v_sub_f32_e32 v138, v153, v134
	v_exp_f32_e32 v203, v138
	v_sub_f32_e32 v138, v156, v134
	v_exp_f32_e32 v204, v138
	v_sub_f32_e32 v138, v155, v134
	v_exp_f32_e32 v205, v138
	v_sub_f32_e32 v138, v158, v134
	v_exp_f32_e32 v215, v138
	v_sub_f32_e32 v138, v157, v134
	v_exp_f32_e32 v217, v138
	v_sub_f32_e32 v138, v159, v134
	v_exp_f32_e32 v230, v138
	v_lshl_or_b32 v138, s0, 6, v225
	v_add_u32_e32 v138, s35, v138
	v_mad_i32_i24 v231, v138, s31, v222
	v_pk_mul_f32 v[178:179], v[112:113], v[176:177] op_sel_hi:[1,0]
	v_pk_mul_f32 v[180:181], v[110:111], v[176:177] op_sel_hi:[1,0]
	v_pk_mul_f32 v[184:185], v[114:115], v[176:177] op_sel_hi:[1,0]
	v_pk_mul_f32 v[186:187], v[120:121], v[176:177] op_sel_hi:[1,0]
	v_pk_mul_f32 v[188:189], v[118:119], v[176:177] op_sel_hi:[1,0]
	v_pk_mul_f32 v[190:191], v[124:125], v[176:177] op_sel_hi:[1,0]
	v_pk_mul_f32 v[192:193], v[122:123], v[176:177] op_sel_hi:[1,0]
	v_pk_mul_f32 v[118:119], v[162:163], v[176:177] op_sel_hi:[1,0]
	v_pk_mul_f32 v[122:123], v[160:161], v[176:177] op_sel_hi:[1,0]
	v_pk_mul_f32 v[120:121], v[166:167], v[176:177] op_sel_hi:[1,0]
	v_pk_mul_f32 v[124:125], v[164:165], v[176:177] op_sel_hi:[1,0]
	v_pk_mul_f32 v[110:111], v[170:171], v[176:177] op_sel_hi:[1,0]
	v_pk_mul_f32 v[114:115], v[168:169], v[176:177] op_sel_hi:[1,0]
	v_cvt_pk_bf16_f32 v152, v180, v181
	v_cvt_pk_bf16_f32 v153, v178, v179
	v_cvt_pk_bf16_f32 v154, v184, v185
	v_cvt_pk_bf16_f32 v155, v182, v183
	ds_read_b64_tr_b16 v[158:159], v231 offset:2560
	ds_read_b64_tr_b16 v[156:157], v231
	ds_read_b64_tr_b16 v[162:163], v231 offset:2592
	ds_read_b64_tr_b16 v[160:161], v231 offset:32
	ds_read_b64_tr_b16 v[164:165], v231 offset:64
	ds_read_b64_tr_b16 v[168:169], v231 offset:96
	ds_read_b64_tr_b16 v[166:167], v231 offset:2624
	ds_read_b64_tr_b16 v[170:171], v231 offset:2656
	v_add_f32_e32 v135, v196, v135
	v_sub_f32_e32 v138, v148, v134
	v_pk_mul_f32 v[112:113], v[174:175], v[176:177] op_sel_hi:[1,0]
	v_pk_mul_f32 v[116:117], v[172:173], v[176:177] op_sel_hi:[1,0]
	v_add_f32_e32 v135, v197, v135
	v_exp_f32_e32 v184, v138
	v_sub_f32_e32 v138, v150, v134
	s_waitcnt lgkmcnt(4)
; #define LAS __attribute__((address_space(3)))
; __device__ __forceinline__ s16x4 vtr(const LAS unsigned char* p) { return __builtin_bit_cast(s16x4, __builtin_amdgcn_ds_read_tr16_b64_v4i16((LAS v4i16_t*)p)); }
; __device__ __forceinline__ bf16x8 cat44(s16x4 lo, s16x4 hi) { return (bf16x8){lo[0], lo[1], lo[2], lo[3], hi[0], hi[1], hi[2], hi[3]}; }
; __device__ __forceinline__ void mixC_mfma(const bf16* P, const float* rpb  , bf16* MIX, LAS unsigned char* lds, int bid, int G, int tid) {
;     ...
;             for (int t = 0; t < 4; ++t) { const float p = __builtin_amdgcn_exp2f(S[kt][t] - mx); S[kt][t] = p; den += p; }
;         den += __shfl_xor(den, 16); den += __shfl_xor(den, 32);
;         f32x4 O[4];
; #pragma unroll
;         for (int dt = 0; dt < 4; ++dt) O[dt] = (f32x4){0.f, 0.f, 0.f, 0.f};
;         const LAS unsigned char* vb = Vs + ((rs - R0) * 64 + kcol0 + 4 * fq + (fr >> 2)) * VROW + 8 * (lane & 3);
; #pragma unroll
;         for (int p = 0; p < 8; ++p) {
;             const bf16x8 Pf = pack_p(S[2 * p], S[2 * p + 1]);
; #pragma unroll
;             for (int dt = 0; dt < 4; ++dt) {
;                 const s16x4 lo = vtr(vb + p * 64 * VROW + dt * 32), hi = vtr(vb + p * 64 * VROW + 16 * VROW + dt * 32);
;                 O[dt] = __builtin_amdgcn_mfma_f32_16x16x32_bf16(cat44(lo, hi), Pf, O[dt], 0, 0, 0);
;             }
	v_mfma_f32_16x16x32_bf16 v[148:151], v[160:163], v[152:155], 0
	v_add_f32_e32 v135, v198, v135
	v_add_f32_e32 v135, v199, v135
	v_add_f32_e32 v135, v200, v135
	s_waitcnt lgkmcnt(1)
	v_mfma_f32_16x16x32_bf16 v[160:163], v[164:167], v[152:155], 0
	v_cvt_pk_bf16_f32 v164, v188, v189
	v_cvt_pk_bf16_f32 v165, v186, v187
	v_cvt_pk_bf16_f32 v166, v192, v193
	v_cvt_pk_bf16_f32 v167, v190, v191
	ds_read_b64_tr_b16 v[174:175], v231 offset:12800
	ds_read_b64_tr_b16 v[172:173], v231 offset:10240
	v_mfma_f32_16x16x32_bf16 v[156:159], v[156:159], v[152:155], 0
	v_exp_f32_e32 v185, v138
	v_sub_f32_e32 v138, v146, v134
	v_add_f32_e32 v135, v201, v135
	s_waitcnt lgkmcnt(2)
	v_mfma_f32_16x16x32_bf16 v[152:155], v[168:171], v[152:155], 0
	ds_read_b64_tr_b16 v[170:171], v231 offset:12832
	ds_read_b64_tr_b16 v[168:169], v231 offset:10272
	ds_read_b64_tr_b16 v[176:177], v231 offset:10304
	ds_read_b64_tr_b16 v[180:181], v231 offset:10336
	ds_read_b64_tr_b16 v[178:179], v231 offset:12864
	ds_read_b64_tr_b16 v[182:183], v231 offset:12896
	v_exp_f32_e32 v186, v138
	v_sub_f32_e32 v138, v142, v134
	v_cvt_pk_bf16_f32 v122, v122, v123
	v_cvt_pk_bf16_f32 v123, v118, v119
	v_cvt_pk_bf16_f32 v124, v124, v125
	v_cvt_pk_bf16_f32 v125, v120, v121
	ds_read_b64_tr_b16 v[120:121], v231 offset:23040
	ds_read_b64_tr_b16 v[118:119], v231 offset:20480
	v_add_f32_e32 v135, v202, v135
	s_waitcnt lgkmcnt(8)
	v_mfma_f32_16x16x32_bf16 v[156:159], v[172:175], v[164:167], v[156:159]
	v_exp_f32_e32 v172, v138
	v_sub_f32_e32 v138, v140, v134
	v_add_f32_e32 v135, v203, v135
	s_waitcnt lgkmcnt(6)
	v_mfma_f32_16x16x32_bf16 v[142:145], v[168:171], v[164:167], v[148:151]
	v_exp_f32_e32 v173, v138
	v_sub_f32_e32 v138, v147, v134
	v_add_f32_e32 v135, v204, v135
	s_waitcnt lgkmcnt(3)
	v_mfma_f32_16x16x32_bf16 v[146:149], v[176:179], v[164:167], v[160:163]
	v_add_f32_e32 v135, v205, v135
	v_add_f32_e32 v135, v215, v135
	v_add_f32_e32 v135, v217, v135
	s_waitcnt lgkmcnt(2)
	v_mfma_f32_16x16x32_bf16 v[150:153], v[180:183], v[164:167], v[152:155]
	ds_read_b64_tr_b16 v[162:163], v231 offset:23072
	ds_read_b64_tr_b16 v[160:161], v231 offset:20512
	ds_read_b64_tr_b16 v[164:165], v231 offset:20544
	ds_read_b64_tr_b16 v[168:169], v231 offset:20576
	ds_read_b64_tr_b16 v[166:167], v231 offset:23104
	ds_read_b64_tr_b16 v[170:171], v231 offset:23136
	v_cvt_pk_bf16_f32 v114, v114, v115
	v_cvt_pk_bf16_f32 v115, v110, v111
	v_cvt_pk_bf16_f32 v116, v116, v117
	v_cvt_pk_bf16_f32 v117, v112, v113
	ds_read_b64_tr_b16 v[112:113], v231 offset:33280
	ds_read_b64_tr_b16 v[110:111], v231 offset:30720
	s_waitcnt lgkmcnt(8)
	v_mfma_f32_16x16x32_bf16 v[118:121], v[118:121], v[122:125], v[156:159]
	v_sub_f32_e32 v136, v136, v134
	v_add_f32_e32 v135, v230, v135
	v_exp_f32_e32 v174, v138
	s_waitcnt lgkmcnt(6)
	v_mfma_f32_16x16x32_bf16 v[142:145], v[160:163], v[122:125], v[142:145]
	v_exp_f32_e32 v158, v136
	v_sub_f32_e32 v136, v141, v134
	v_add_f32_e32 v135, v184, v135
	s_waitcnt lgkmcnt(3)
	v_mfma_f32_16x16x32_bf16 v[138:141], v[164:167], v[122:125], v[146:149]
	v_add_f32_e32 v135, v185, v135
	v_add_f32_e32 v135, v186, v135
	v_add_f32_e32 v135, v172, v135
	s_waitcnt lgkmcnt(2)
	v_mfma_f32_16x16x32_bf16 v[122:125], v[168:171], v[122:125], v[150:153]
	ds_read_b64_tr_b16 v[148:149], v231 offset:33312
	ds_read_b64_tr_b16 v[146:147], v231 offset:30752
	s_nop 0
	ds_read_b64_tr_b16 v[150:151], v231 offset:30784
	ds_read_b64_tr_b16 v[154:155], v231 offset:30816
	ds_read_b64_tr_b16 v[152:153], v231 offset:33344
	ds_read_b64_tr_b16 v[156:157], v231 offset:33376
	v_exp_f32_e32 v159, v136
	v_add_f32_e32 v135, v173, v135
	s_waitcnt lgkmcnt(6)
	v_mfma_f32_16x16x32_bf16 v[110:113], v[110:113], v[114:117], v[118:121]
	v_add_f32_e32 v135, v174, v135
	v_sub_f32_e32 v128, v128, v134
	v_add_f32_e32 v135, v158, v135
	v_sub_f32_e32 v118, v131, v134
	v_exp_f32_e32 v131, v118
	s_waitcnt lgkmcnt(4)
	v_mfma_f32_16x16x32_bf16 v[118:121], v[146:149], v[114:117], v[142:145]
	v_sub_f32_e32 v148, v137, v134
	v_exp_f32_e32 v160, v148
	v_add_f32_e32 v135, v159, v135
	s_waitcnt lgkmcnt(1)
	v_mfma_f32_16x16x32_bf16 v[136:139], v[150:153], v[114:117], v[138:141]
	v_cvt_pk_bf16_f32 v140, v194, v195
	v_cvt_pk_bf16_f32 v141, v196, v197
	v_cvt_pk_bf16_f32 v142, v198, v199
	v_cvt_pk_bf16_f32 v143, v200, v201
	ds_read_b64_tr_b16 v[146:147], v231 offset:43520
	ds_read_b64_tr_b16 v[144:145], v231 offset:40960
	s_waitcnt lgkmcnt(2)
	v_mfma_f32_16x16x32_bf16 v[114:117], v[154:157], v[114:117], v[122:125]
	s_nop 2
	ds_read_b64_tr_b16 v[124:125], v231 offset:43552
	ds_read_b64_tr_b16 v[122:123], v231 offset:40992
	ds_read_b64_tr_b16 v[148:149], v231 offset:41024
	ds_read_b64_tr_b16 v[152:153], v231 offset:41056
	ds_read_b64_tr_b16 v[150:151], v231 offset:43584
	ds_read_b64_tr_b16 v[154:155], v231 offset:43616
	v_exp_f32_e32 v156, v128
	v_sub_f32_e32 v128, v132, v134
	s_waitcnt lgkmcnt(4)
	v_mfma_f32_16x16x32_bf16 v[118:121], v[122:125], v[140:143], v[118:121]
	v_sub_f32_e32 v122, v133, v134
	v_exp_f32_e32 v133, v122
	v_add_f32_e32 v135, v131, v135
	v_mfma_f32_16x16x32_bf16 v[110:113], v[144:147], v[140:143], v[110:113]
	v_exp_f32_e32 v157, v128
	v_add_f32_e32 v135, v160, v135
	v_add_f32_e32 v128, v156, v135
	s_waitcnt lgkmcnt(1)
	v_mfma_f32_16x16x32_bf16 v[122:125], v[148:151], v[140:143], v[136:139]
	v_cvt_pk_bf16_f32 v136, v202, v203
	v_cvt_pk_bf16_f32 v137, v204, v205
	v_cvt_pk_bf16_f32 v138, v215, v217
	v_cvt_pk_bf16_f32 v139, v230, v184
	ds_read_b64_tr_b16 v[146:147], v231 offset:53760
	ds_read_b64_tr_b16 v[144:145], v231 offset:51200
	s_waitcnt lgkmcnt(2)
; __device__ __forceinline__ s16x4 vtr(const LAS unsigned char* p) { return __builtin_bit_cast(s16x4, __builtin_amdgcn_ds_read_tr16_b64_v4i16((LAS v4i16_t*)p)); }
; __device__ __forceinline__ unsigned cvtpk(float lo, float hi) { unsigned r; asm volatile("v_cvt_pk_bf16_f32 %0, %1, %2" : "=v"(r) : "v"(lo), "v"(hi)); return r; }
; __device__ __forceinline__ bf16x8 cat44(s16x4 lo, s16x4 hi) { return (bf16x8){lo[0], lo[1], lo[2], lo[3], hi[0], hi[1], hi[2], hi[3]}; }
; __device__ __forceinline__ void mixC_mfma(const bf16* P, const float* rpb  , bf16* MIX, LAS unsigned char* lds, int bid, int G, int tid) {
;     ...
;             for (int dt = 0; dt < 4; ++dt) {
;                 const s16x4 lo = vtr(vb + p * 64 * VROW + dt * 32), hi = vtr(vb + p * 64 * VROW + 16 * VROW + dt * 32);
;                 O[dt] = __builtin_amdgcn_mfma_f32_16x16x32_bf16(cat44(lo, hi), Pf, O[dt], 0, 0, 0);
;             }
;         }
;         const float inv = 1.0f / den;
;         bf16* op = MIX + qrow * DMIX + 768 + h * 64 + 4 * fq;
; #pragma unroll
;         for (int dt = 0; dt < 4; ++dt) { v2u w; w.x = cvtpk(O[dt][0] * inv, O[dt][1] * inv); w.y = cvtpk(O[dt][2] * inv, O[dt][3] * inv); *(v2u*)(op + 16 * dt) = w; }
	v_mfma_f32_16x16x32_bf16 v[114:117], v[152:155], v[140:143], v[114:117]
	ds_read_b64_tr_b16 v[142:143], v231 offset:53792
	ds_read_b64_tr_b16 v[140:141], v231 offset:51232
	ds_read_b64_tr_b16 v[148:149], v231 offset:51264
	ds_read_b64_tr_b16 v[152:153], v231 offset:51296
	ds_read_b64_tr_b16 v[150:151], v231 offset:53824
	ds_read_b64_tr_b16 v[154:155], v231 offset:53856
	v_add_f32_e32 v128, v133, v128
	v_add_f32_e32 v132, v157, v128
	v_sub_f32_e32 v128, v130, v134
	s_waitcnt lgkmcnt(6)
	v_mfma_f32_16x16x32_bf16 v[110:113], v[144:147], v[136:139], v[110:113]
	v_exp_f32_e32 v135, v128
	v_sub_f32_e32 v144, v129, v134
	v_cvt_pk_bf16_f32 v128, v185, v186
	s_waitcnt lgkmcnt(4)
	v_mfma_f32_16x16x32_bf16 v[118:121], v[140:143], v[136:139], v[118:121]
	v_cvt_pk_bf16_f32 v129, v172, v173
	v_cvt_pk_bf16_f32 v130, v174, v158
	v_cvt_pk_bf16_f32 v131, v159, v131
	ds_read_b64_tr_b16 v[142:143], v231 offset:64000
	ds_read_b64_tr_b16 v[140:141], v231 offset:61440
	v_exp_f32_e32 v158, v144
	v_sub_f32_e32 v127, v127, v134
	v_exp_f32_e32 v127, v127
	v_sub_f32_e32 v126, v126, v134
	s_waitcnt lgkmcnt(3)
	v_mfma_f32_16x16x32_bf16 v[122:125], v[148:151], v[136:139], v[122:125]
	v_exp_f32_e32 v126, v126
	v_add_f32_e32 v132, v135, v132
	s_lshl_b32 s4, s90, 6
	s_waitcnt lgkmcnt(2)
	v_mfma_f32_16x16x32_bf16 v[114:117], v[152:155], v[136:139], v[114:117]
	ds_read_b64_tr_b16 v[138:139], v231 offset:64032
	ds_read_b64_tr_b16 v[136:137], v231 offset:61472
	ds_read_b64_tr_b16 v[144:145], v231 offset:61504
	ds_read_b64_tr_b16 v[148:149], v231 offset:61536
	ds_read_b64_tr_b16 v[146:147], v231 offset:64064
	ds_read_b64_tr_b16 v[150:151], v231 offset:64096
	s_add_i32 s4, s4, s89
	v_mov_b32_e32 v217, v211
	s_waitcnt lgkmcnt(6)
	v_mfma_f32_16x16x32_bf16 v[110:113], v[140:143], v[128:131], v[110:113]
	v_add_f32_e32 v140, v158, v132
	v_cvt_pk_bf16_f32 v132, v160, v156
	v_cvt_pk_bf16_f32 v133, v133, v157
	v_cvt_pk_bf16_f32 v134, v135, v158
	v_cvt_pk_bf16_f32 v135, v127, v126
	v_add_f32_e32 v127, v127, v140
	s_waitcnt lgkmcnt(4)
	v_mfma_f32_16x16x32_bf16 v[118:121], v[136:139], v[128:131], v[118:121]
	v_add_u32_e32 v136, 0x11800, v231
	v_add_u32_e32 v138, 0x12200, v231
	v_add_f32_e32 v140, v126, v127
	s_waitcnt lgkmcnt(1)
	v_mfma_f32_16x16x32_bf16 v[122:125], v[144:147], v[128:131], v[122:125]
	ds_read_b64_tr_b16 v[136:137], v136
	ds_read_b64_tr_b16 v[138:139], v138
	v_add_u32_e32 v126, 0x11820, v231
	s_add_i32 s34, s34, s33
	s_waitcnt lgkmcnt(2)
	v_mfma_f32_16x16x32_bf16 v[114:117], v[148:151], v[128:131], v[114:117]
	ds_bpermute_b32 v130, v219, v140
	v_add_u32_e32 v128, 0x12220, v231
	v_add_u32_e32 v131, 0x11840, v231
	s_waitcnt lgkmcnt(1)
	v_mfma_f32_16x16x32_bf16 v[110:113], v[136:139], v[132:135], v[110:113]
	v_add_u32_e32 v138, 0x12240, v231
	s_waitcnt lgkmcnt(0)
	v_add_f32_e32 v130, v140, v130
	ds_read_b64_tr_b16 v[126:127], v126
	ds_read_b64_tr_b16 v[128:129], v128
	ds_read_b64_tr_b16 v[136:137], v131
	ds_read_b64_tr_b16 v[138:139], v138
	ds_bpermute_b32 v131, v220, v130
	s_waitcnt lgkmcnt(3)
	v_mfma_f32_16x16x32_bf16 v[118:121], v[126:129], v[132:135], v[118:121]
	v_add_u32_e32 v126, 0x11860, v231
	v_add_u32_e32 v128, 0x12260, v231
	s_waitcnt lgkmcnt(0)
	v_add_f32_e32 v130, v130, v131
	ds_read_b64_tr_b16 v[126:127], v126
	ds_read_b64_tr_b16 v[128:129], v128
	v_div_scale_f32 v131, s[0:1], v130, v130, 1.0
	v_mfma_f32_16x16x32_bf16 v[122:125], v[136:139], v[132:135], v[122:125]
	v_rcp_f32_e32 v136, v131
	v_or_b32_e32 v137, s4, v1
	s_movk_i32 s0, 0xc00
	s_waitcnt lgkmcnt(0)
	v_mfma_f32_16x16x32_bf16 v[114:117], v[126:129], v[132:135], v[114:117]
	v_fma_f32 v126, -v131, v136, 1.0
	v_fmac_f32_e32 v136, v126, v136
	v_div_scale_f32 v126, vcc, 1.0, v130, 1.0
	v_mul_f32_e32 v127, v126, v136
	v_fma_f32 v128, -v131, v127, v126
	v_fmac_f32_e32 v127, v128, v136
	v_fma_f32 v126, -v131, v127, v126
	v_div_fmas_f32 v126, v126, v136, v127
	v_div_fixup_f32 v128, v126, v130, 1.0
	v_mov_b64_e32 v[126:127], s[76:77]
	v_mad_i64_i32 v[126:127], s[0:1], v137, s0, v[126:127]
	v_mul_f32_e32 v110, v128, v110
	v_mul_f32_e32 v111, v128, v111
	v_lshl_add_u64 v[126:127], s[80:81], 1, v[126:127]
	v_cvt_pk_bf16_f32 v110, v110, v111
	v_mul_f32_e32 v111, v128, v112
	v_lshl_add_u64 v[126:127], v[126:127], 0, v[216:217]
	v_mul_f32_e32 v112, v128, v113
	v_cvt_pk_bf16_f32 v111, v111, v112
	v_mul_f32_e32 v112, v128, v118
	v_mul_f32_e32 v113, v128, v119
	v_cvt_pk_bf16_f32 v112, v112, v113
	v_mul_f32_e32 v113, v128, v120
	v_mul_f32_e32 v118, v128, v121
	v_cvt_pk_bf16_f32 v113, v113, v118
	v_bfe_u32 v250, v208, 4, 1
	v_mul_u32_u24_e32 v250, 24, v250
	v_mov_b32_e32 v251, 0
	v_lshl_add_u64 v[126:127], v[126:127], 0, v[250:251]
	v_permlane16_swap_b32 v110, v112
	v_permlane16_swap_b32 v111, v113
	global_store_dwordx4 v[126:127], v[110:113], off offset:1536
	v_mul_f32_e32 v118, v128, v122
	v_mul_f32_e32 v119, v128, v123
	v_cvt_pk_bf16_f32 v118, v118, v119
	v_mul_f32_e32 v119, v128, v124
	v_mul_f32_e32 v120, v128, v125
	v_cvt_pk_bf16_f32 v119, v119, v120
	v_mul_f32_e32 v120, v128, v114
	v_mul_f32_e32 v121, v128, v115
	v_cvt_pk_bf16_f32 v120, v120, v121
	v_mul_f32_e32 v121, v128, v116
	s_andn2_b64 vcc, exec, s[82:83]
	v_mul_f32_e32 v122, v128, v117
	v_cvt_pk_bf16_f32 v121, v121, v122
	s_nop 1
	v_permlane16_swap_b32 v118, v120
	v_permlane16_swap_b32 v119, v121
	global_store_dwordx4 v[126:127], v[118:121], off offset:1600
	s_cbranch_vccz .LBB0_493

; #define LAS __attribute__((address_space(3)))
; __device__ __forceinline__ void mixC_mfma(const bf16* P, const float* rpb  , bf16* MIX, LAS unsigned char* lds, int bid, int G, int tid) {
;     ...
;         m1 = fmaxf(m1, __shfl_xor(m1, 16)); m1 = fmaxf(m1, __shfl_xor(m1, 32));
;         float l1 = 0.f;
; #pragma unroll
;         for (int kt = 0; kt < 8; ++kt)
; #pragma unroll
;             for (int t = 0; t < 4; ++t) { const float p = __builtin_amdgcn_exp2f(S[kt][t] - m1); S[kt][t] = p; l1 += p; }
; #pragma unroll
;         for (int kt = 8; kt < 16; ++kt) { f32x4 z = {0.f, 0.f, 0.f, 0.f};
;             z = __builtin_amdgcn_mfma_f32_16x16x32_bf16(Kl[kt - 8][0], Qn0, z, 0, 0, 0);
;             S[kt] = __builtin_amdgcn_mfma_f32_16x16x32_bf16(Kl[kt - 8][1], Qn1, z, 0, 0, 0); }
;         asm volatile("" ::: "memory");
;         if (un + G < NU) c_prefetch(P, un + G, tid, wave, fr, fq, vpre, Qn0, Qn1, Kn);
;         float mx = m1;
; #pragma unroll
;         for (int kt = 8; kt < 16; ++kt)
; #pragma unroll
;             for (int t = 0; t < 4; ++t) {
;                 const bool ok = (unsigned)(d0 + 16 * (kt & 1) + t) < 16u;
;                 const float sv = ok ? S[kt][t] * (0.125f * L2E) + rpl[(kt >> 1) * 31 + 16 * (kt & 1) + t] : -1e30f;
;                 S[kt][t] = sv; mx = fmaxf(mx, sv);
;             }
;         mx = fmaxf(mx, __shfl_xor(mx, 16)); mx = fmaxf(mx, __shfl_xor(mx, 32));
;         const float sc1 = __builtin_amdgcn_exp2f(m1 - mx);
;         float den = l1 * sc1;
; #pragma unroll
;         for (int kt = 0; kt < 8; ++kt) S[kt] = S[kt] * sc1;
; #pragma unroll
;         for (int kt = 8; kt < 16; ++kt)
; #pragma unroll
;             for (int t = 0; t < 4; ++t) { const float p = __builtin_amdgcn_exp2f(S[kt][t] - mx); S[kt][t] = p; den += p; }
;         den += __shfl_xor(den, 16); den += __shfl_xor(den, 32);
;         f32x4 O[4];
; #pragma unroll
;         for (int dt = 0; dt < 4; ++dt) O[dt] = (f32x4){0.f, 0.f, 0.f, 0.f};
;         const LAS unsigned char* vb = Vs + ((rs - R0) * 64 + kcol0 + 4 * fq + (fr >> 2)) * VROW + 8 * (lane & 3);
; #pragma unroll
;         for (int p = 0; p < 8; ++p) {
;             const bf16x8 Pf = pack_p(S[2 * p], S[2 * p + 1]);
.LBB0_1377:
	s_or_b64 exec, exec, s[0:1]
	s_waitcnt lgkmcnt(0)
	v_max_f32_e32 v110, v135, v135
	v_max_f32_e32 v111, v134, v134
	v_max_f32_e32 v135, v111, v110
	v_max3_f32 v110, v135, v139, v138
	v_max3_f32 v110, v110, v144, v143
	v_max3_f32 v110, v110, v149, v145
	v_max3_f32 v110, v110, v152, v151
	v_max3_f32 v110, v110, v154, v153
	v_max3_f32 v110, v110, v156, v155
	v_max3_f32 v110, v110, v158, v157
	v_max3_f32 v110, v110, v159, v148
	v_max3_f32 v110, v110, v150, v146
	v_max3_f32 v110, v110, v142, v140
	v_max3_f32 v110, v110, v147, v136
	v_max3_f32 v110, v110, v141, v131
	v_max3_f32 v110, v110, v137, v128
	v_max3_f32 v110, v110, v133, v132
	v_max3_f32 v134, v110, v130, v129
	v_sub_f32_e32 v110, v230, v135
	v_exp_f32_e32 v110, v110
	v_sub_f32_e32 v111, v217, v135
	v_exp_f32_e32 v111, v111
	v_sub_f32_e32 v112, v203, v135
	v_exp_f32_e32 v112, v112
	v_sub_f32_e32 v113, v202, v135
	v_exp_f32_e32 v113, v113
	v_add_f32_e32 v114, 0, v110
	v_add_f32_e32 v114, v111, v114
	v_add_f32_e32 v114, v112, v114
	v_add_f32_e32 v118, v113, v114
	v_sub_f32_e32 v114, v205, v135
	v_exp_f32_e32 v114, v114
	v_sub_f32_e32 v115, v204, v135
	v_exp_f32_e32 v115, v115
	v_sub_f32_e32 v116, v199, v135
	v_exp_f32_e32 v116, v116
	v_sub_f32_e32 v117, v198, v135
	v_exp_f32_e32 v117, v117
	v_add_f32_e32 v118, v114, v118
	v_add_f32_e32 v118, v115, v118
	v_add_f32_e32 v118, v116, v118
	v_add_f32_e32 v122, v117, v118
	v_sub_f32_e32 v118, v201, v135
	v_exp_f32_e32 v118, v118
	v_sub_f32_e32 v119, v200, v135
	v_exp_f32_e32 v119, v119
	v_sub_f32_e32 v120, v195, v135
	v_exp_f32_e32 v120, v120
	v_sub_f32_e32 v121, v194, v135
	v_exp_f32_e32 v121, v121
	v_add_f32_e32 v122, v118, v122
	v_add_f32_e32 v122, v119, v122
	v_add_f32_e32 v122, v120, v122
	v_add_f32_e32 v160, v121, v122
	v_sub_f32_e32 v122, v197, v135
	v_exp_f32_e32 v122, v122
	v_sub_f32_e32 v123, v196, v135
	v_exp_f32_e32 v123, v123
	v_sub_f32_e32 v124, v191, v135
	v_exp_f32_e32 v124, v124
	v_sub_f32_e32 v125, v190, v135
	v_exp_f32_e32 v125, v125
	v_add_f32_e32 v160, v122, v160
	v_add_f32_e32 v160, v123, v160
	v_add_f32_e32 v160, v124, v160
	v_add_f32_e32 v164, v125, v160
	v_sub_f32_e32 v160, v193, v135
	v_exp_f32_e32 v160, v160
	v_sub_f32_e32 v161, v192, v135
	v_exp_f32_e32 v161, v161
	v_sub_f32_e32 v162, v187, v135
	v_exp_f32_e32 v162, v162
	v_sub_f32_e32 v163, v186, v135
	v_exp_f32_e32 v163, v163
	v_add_f32_e32 v164, v160, v164
	v_add_f32_e32 v164, v161, v164
	v_add_f32_e32 v164, v162, v164
	v_add_f32_e32 v168, v163, v164
	v_sub_f32_e32 v164, v189, v135
	v_exp_f32_e32 v164, v164
	v_sub_f32_e32 v165, v188, v135
	v_exp_f32_e32 v165, v165
	v_sub_f32_e32 v166, v183, v135
	v_exp_f32_e32 v166, v166
	v_sub_f32_e32 v167, v182, v135
	v_exp_f32_e32 v167, v167
	v_add_f32_e32 v168, v164, v168
	v_add_f32_e32 v168, v165, v168
	v_add_f32_e32 v168, v166, v168
	v_add_f32_e32 v172, v167, v168
	v_sub_f32_e32 v168, v185, v135
	v_max3_f32 v134, v134, v127, v126
	v_exp_f32_e32 v168, v168
	v_sub_f32_e32 v169, v184, v135
	ds_bpermute_b32 v174, v219, v134
	v_exp_f32_e32 v169, v169
	v_sub_f32_e32 v170, v233, v135
	v_exp_f32_e32 v170, v170
	v_sub_f32_e32 v171, v232, v135
	v_exp_f32_e32 v171, v171
	v_add_f32_e32 v172, v168, v172
	v_add_f32_e32 v172, v169, v172
	s_waitcnt lgkmcnt(0)
	v_max_f32_e32 v174, v174, v174
	v_add_f32_e32 v172, v170, v172
	v_max_f32_e32 v134, v134, v174
	v_add_f32_e32 v176, v171, v172
	v_sub_f32_e32 v172, v235, v135
	ds_bpermute_b32 v177, v220, v134
	v_exp_f32_e32 v172, v172
	v_sub_f32_e32 v175, v237, v135
	v_sub_f32_e32 v173, v234, v135
	v_exp_f32_e32 v174, v175
	v_add_f32_e32 v178, v172, v176
	s_waitcnt lgkmcnt(0)
	v_max_f32_e32 v176, v177, v177
	v_max_f32_e32 v134, v134, v176
	v_sub_f32_e32 v175, v236, v135
	v_sub_f32_e32 v135, v135, v134
	v_exp_f32_e32 v176, v135
	v_exp_f32_e32 v173, v173
	v_exp_f32_e32 v175, v175
	s_sub_i32 s0, s86, s84
	v_pk_mul_f32 v[182:183], v[116:117], v[176:177] op_sel_hi:[1,0]
	v_sub_f32_e32 v116, v139, v134
	v_exp_f32_e32 v194, v116
	v_sub_f32_e32 v116, v138, v134
	v_add_f32_e32 v135, v173, v178
	v_exp_f32_e32 v195, v116
	v_add_f32_e32 v135, v174, v135
	v_add_f32_e32 v135, v175, v135
	v_mov_b32_e32 v138, v194
	v_fmac_f32_e32 v138, v135, v176
	v_add_f32_e32 v135, v195, v138
	v_sub_f32_e32 v138, v144, v134
	v_exp_f32_e32 v196, v138
	v_sub_f32_e32 v138, v143, v134
	v_exp_f32_e32 v197, v138
	v_sub_f32_e32 v138, v149, v134
	v_exp_f32_e32 v198, v138
	v_sub_f32_e32 v138, v145, v134
	v_exp_f32_e32 v199, v138
	v_sub_f32_e32 v138, v152, v134
	v_exp_f32_e32 v200, v138
	v_sub_f32_e32 v138, v151, v134
	v_exp_f32_e32 v201, v138
	v_sub_f32_e32 v138, v154, v134
	v_exp_f32_e32 v202, v138
	v_sub_f32_e32 v138, v153, v134
	v_exp_f32_e32 v203, v138
	v_sub_f32_e32 v138, v156, v134
	v_exp_f32_e32 v204, v138
	v_sub_f32_e32 v138, v155, v134
	v_exp_f32_e32 v205, v138
	v_sub_f32_e32 v138, v158, v134
	v_exp_f32_e32 v215, v138
	v_sub_f32_e32 v138, v157, v134
	v_exp_f32_e32 v217, v138
	v_sub_f32_e32 v138, v159, v134
	v_exp_f32_e32 v230, v138
	v_lshl_or_b32 v138, s0, 6, v225
	v_add_u32_e32 v138, s85, v138
	v_mad_i32_i24 v231, v138, s53, v222
	v_pk_mul_f32 v[178:179], v[112:113], v[176:177] op_sel_hi:[1,0]
	v_pk_mul_f32 v[180:181], v[110:111], v[176:177] op_sel_hi:[1,0]
	v_pk_mul_f32 v[184:185], v[114:115], v[176:177] op_sel_hi:[1,0]
	v_pk_mul_f32 v[186:187], v[120:121], v[176:177] op_sel_hi:[1,0]
	v_pk_mul_f32 v[188:189], v[118:119], v[176:177] op_sel_hi:[1,0]
	v_pk_mul_f32 v[190:191], v[124:125], v[176:177] op_sel_hi:[1,0]
	v_pk_mul_f32 v[192:193], v[122:123], v[176:177] op_sel_hi:[1,0]
	v_pk_mul_f32 v[118:119], v[162:163], v[176:177] op_sel_hi:[1,0]
	v_pk_mul_f32 v[122:123], v[160:161], v[176:177] op_sel_hi:[1,0]
	v_pk_mul_f32 v[120:121], v[166:167], v[176:177] op_sel_hi:[1,0]
	v_pk_mul_f32 v[124:125], v[164:165], v[176:177] op_sel_hi:[1,0]
	v_pk_mul_f32 v[110:111], v[170:171], v[176:177] op_sel_hi:[1,0]
	v_pk_mul_f32 v[114:115], v[168:169], v[176:177] op_sel_hi:[1,0]
	v_cvt_pk_bf16_f32 v152, v180, v181
	v_cvt_pk_bf16_f32 v153, v178, v179
	v_cvt_pk_bf16_f32 v154, v184, v185
	v_cvt_pk_bf16_f32 v155, v182, v183
	ds_read_b64_tr_b16 v[158:159], v231 offset:2560
	ds_read_b64_tr_b16 v[156:157], v231
	ds_read_b64_tr_b16 v[162:163], v231 offset:2592
	ds_read_b64_tr_b16 v[160:161], v231 offset:32
	ds_read_b64_tr_b16 v[164:165], v231 offset:64
	ds_read_b64_tr_b16 v[168:169], v231 offset:96
	ds_read_b64_tr_b16 v[166:167], v231 offset:2624
	ds_read_b64_tr_b16 v[170:171], v231 offset:2656
	v_add_f32_e32 v135, v196, v135
	v_sub_f32_e32 v138, v148, v134
	v_pk_mul_f32 v[112:113], v[174:175], v[176:177] op_sel_hi:[1,0]
	v_pk_mul_f32 v[116:117], v[172:173], v[176:177] op_sel_hi:[1,0]
	v_add_f32_e32 v135, v197, v135
	v_exp_f32_e32 v184, v138
	v_sub_f32_e32 v138, v150, v134
	s_waitcnt lgkmcnt(4)
; #define LAS __attribute__((address_space(3)))
; __device__ __forceinline__ s16x4 vtr(const LAS unsigned char* p) { return __builtin_bit_cast(s16x4, __builtin_amdgcn_ds_read_tr16_b64_v4i16((LAS v4i16_t*)p)); }
; __device__ __forceinline__ bf16x8 cat44(s16x4 lo, s16x4 hi) { return (bf16x8){lo[0], lo[1], lo[2], lo[3], hi[0], hi[1], hi[2], hi[3]}; }
; __device__ __forceinline__ void mixC_mfma(const bf16* P, const float* rpb  , bf16* MIX, LAS unsigned char* lds, int bid, int G, int tid) {
;     ...
;             for (int t = 0; t < 4; ++t) { const float p = __builtin_amdgcn_exp2f(S[kt][t] - mx); S[kt][t] = p; den += p; }
;         den += __shfl_xor(den, 16); den += __shfl_xor(den, 32);
;         f32x4 O[4];
; #pragma unroll
;         for (int dt = 0; dt < 4; ++dt) O[dt] = (f32x4){0.f, 0.f, 0.f, 0.f};
;         const LAS unsigned char* vb = Vs + ((rs - R0) * 64 + kcol0 + 4 * fq + (fr >> 2)) * VROW + 8 * (lane & 3);
; #pragma unroll
;         for (int p = 0; p < 8; ++p) {
;             const bf16x8 Pf = pack_p(S[2 * p], S[2 * p + 1]);
; #pragma unroll
;             for (int dt = 0; dt < 4; ++dt) {
;                 const s16x4 lo = vtr(vb + p * 64 * VROW + dt * 32), hi = vtr(vb + p * 64 * VROW + 16 * VROW + dt * 32);
;                 O[dt] = __builtin_amdgcn_mfma_f32_16x16x32_bf16(cat44(lo, hi), Pf, O[dt], 0, 0, 0);
;             }
	v_mfma_f32_16x16x32_bf16 v[148:151], v[160:163], v[152:155], 0
	v_add_f32_e32 v135, v198, v135
	v_add_f32_e32 v135, v199, v135
	v_add_f32_e32 v135, v200, v135
	s_waitcnt lgkmcnt(1)
	v_mfma_f32_16x16x32_bf16 v[160:163], v[164:167], v[152:155], 0
	v_cvt_pk_bf16_f32 v164, v188, v189
	v_cvt_pk_bf16_f32 v165, v186, v187
	v_cvt_pk_bf16_f32 v166, v192, v193
	v_cvt_pk_bf16_f32 v167, v190, v191
	ds_read_b64_tr_b16 v[174:175], v231 offset:12800
	ds_read_b64_tr_b16 v[172:173], v231 offset:10240
	v_mfma_f32_16x16x32_bf16 v[156:159], v[156:159], v[152:155], 0
	v_exp_f32_e32 v185, v138
	v_sub_f32_e32 v138, v146, v134
	v_add_f32_e32 v135, v201, v135
	s_waitcnt lgkmcnt(2)
	v_mfma_f32_16x16x32_bf16 v[152:155], v[168:171], v[152:155], 0
	ds_read_b64_tr_b16 v[170:171], v231 offset:12832
	ds_read_b64_tr_b16 v[168:169], v231 offset:10272
	ds_read_b64_tr_b16 v[176:177], v231 offset:10304
	ds_read_b64_tr_b16 v[180:181], v231 offset:10336
	ds_read_b64_tr_b16 v[178:179], v231 offset:12864
	ds_read_b64_tr_b16 v[182:183], v231 offset:12896
	v_exp_f32_e32 v186, v138
	v_sub_f32_e32 v138, v142, v134
	v_cvt_pk_bf16_f32 v122, v122, v123
	v_cvt_pk_bf16_f32 v123, v118, v119
	v_cvt_pk_bf16_f32 v124, v124, v125
	v_cvt_pk_bf16_f32 v125, v120, v121
	ds_read_b64_tr_b16 v[120:121], v231 offset:23040
	ds_read_b64_tr_b16 v[118:119], v231 offset:20480
	v_add_f32_e32 v135, v202, v135
	s_waitcnt lgkmcnt(8)
	v_mfma_f32_16x16x32_bf16 v[156:159], v[172:175], v[164:167], v[156:159]
	v_exp_f32_e32 v172, v138
	v_sub_f32_e32 v138, v140, v134
	v_add_f32_e32 v135, v203, v135
	s_waitcnt lgkmcnt(6)
	v_mfma_f32_16x16x32_bf16 v[142:145], v[168:171], v[164:167], v[148:151]
	v_exp_f32_e32 v173, v138
	v_sub_f32_e32 v138, v147, v134
	v_add_f32_e32 v135, v204, v135
	s_waitcnt lgkmcnt(3)
	v_mfma_f32_16x16x32_bf16 v[146:149], v[176:179], v[164:167], v[160:163]
	v_add_f32_e32 v135, v205, v135
	v_add_f32_e32 v135, v215, v135
	v_add_f32_e32 v135, v217, v135
	s_waitcnt lgkmcnt(2)
	v_mfma_f32_16x16x32_bf16 v[150:153], v[180:183], v[164:167], v[152:155]
	ds_read_b64_tr_b16 v[162:163], v231 offset:23072
	ds_read_b64_tr_b16 v[160:161], v231 offset:20512
	ds_read_b64_tr_b16 v[164:165], v231 offset:20544
	ds_read_b64_tr_b16 v[168:169], v231 offset:20576
	ds_read_b64_tr_b16 v[166:167], v231 offset:23104
	ds_read_b64_tr_b16 v[170:171], v231 offset:23136
	v_cvt_pk_bf16_f32 v114, v114, v115
	v_cvt_pk_bf16_f32 v115, v110, v111
	v_cvt_pk_bf16_f32 v116, v116, v117
	v_cvt_pk_bf16_f32 v117, v112, v113
	ds_read_b64_tr_b16 v[112:113], v231 offset:33280
	ds_read_b64_tr_b16 v[110:111], v231 offset:30720
	s_waitcnt lgkmcnt(8)
	v_mfma_f32_16x16x32_bf16 v[118:121], v[118:121], v[122:125], v[156:159]
	v_sub_f32_e32 v136, v136, v134
	v_add_f32_e32 v135, v230, v135
	v_exp_f32_e32 v174, v138
	s_waitcnt lgkmcnt(6)
	v_mfma_f32_16x16x32_bf16 v[142:145], v[160:163], v[122:125], v[142:145]
	v_exp_f32_e32 v158, v136
	v_sub_f32_e32 v136, v141, v134
	v_add_f32_e32 v135, v184, v135
	s_waitcnt lgkmcnt(3)
	v_mfma_f32_16x16x32_bf16 v[138:141], v[164:167], v[122:125], v[146:149]
	v_add_f32_e32 v135, v185, v135
	v_add_f32_e32 v135, v186, v135
	v_add_f32_e32 v135, v172, v135
	s_waitcnt lgkmcnt(2)
	v_mfma_f32_16x16x32_bf16 v[122:125], v[168:171], v[122:125], v[150:153]
	ds_read_b64_tr_b16 v[148:149], v231 offset:33312
	ds_read_b64_tr_b16 v[146:147], v231 offset:30752
	s_nop 0
	ds_read_b64_tr_b16 v[150:151], v231 offset:30784
	ds_read_b64_tr_b16 v[154:155], v231 offset:30816
	ds_read_b64_tr_b16 v[152:153], v231 offset:33344
	ds_read_b64_tr_b16 v[156:157], v231 offset:33376
	v_exp_f32_e32 v159, v136
	v_add_f32_e32 v135, v173, v135
	s_waitcnt lgkmcnt(6)
	v_mfma_f32_16x16x32_bf16 v[110:113], v[110:113], v[114:117], v[118:121]
	v_add_f32_e32 v135, v174, v135
	v_sub_f32_e32 v128, v128, v134
	v_add_f32_e32 v135, v158, v135
	v_sub_f32_e32 v118, v131, v134
	v_exp_f32_e32 v131, v118
	s_waitcnt lgkmcnt(4)
	v_mfma_f32_16x16x32_bf16 v[118:121], v[146:149], v[114:117], v[142:145]
	v_sub_f32_e32 v148, v137, v134
	v_exp_f32_e32 v160, v148
	v_add_f32_e32 v135, v159, v135
	s_waitcnt lgkmcnt(1)
	v_mfma_f32_16x16x32_bf16 v[136:139], v[150:153], v[114:117], v[138:141]
	v_cvt_pk_bf16_f32 v140, v194, v195
	v_cvt_pk_bf16_f32 v141, v196, v197
	v_cvt_pk_bf16_f32 v142, v198, v199
	v_cvt_pk_bf16_f32 v143, v200, v201
	ds_read_b64_tr_b16 v[146:147], v231 offset:43520
	ds_read_b64_tr_b16 v[144:145], v231 offset:40960
	s_waitcnt lgkmcnt(2)
	v_mfma_f32_16x16x32_bf16 v[114:117], v[154:157], v[114:117], v[122:125]
	s_nop 2
	ds_read_b64_tr_b16 v[124:125], v231 offset:43552
	ds_read_b64_tr_b16 v[122:123], v231 offset:40992
	ds_read_b64_tr_b16 v[148:149], v231 offset:41024
	ds_read_b64_tr_b16 v[152:153], v231 offset:41056
	ds_read_b64_tr_b16 v[150:151], v231 offset:43584
	ds_read_b64_tr_b16 v[154:155], v231 offset:43616
	v_exp_f32_e32 v156, v128
	v_sub_f32_e32 v128, v132, v134
	s_waitcnt lgkmcnt(4)
	v_mfma_f32_16x16x32_bf16 v[118:121], v[122:125], v[140:143], v[118:121]
	v_sub_f32_e32 v122, v133, v134
	v_exp_f32_e32 v133, v122
	v_add_f32_e32 v135, v131, v135
	v_mfma_f32_16x16x32_bf16 v[110:113], v[144:147], v[140:143], v[110:113]
	v_exp_f32_e32 v157, v128
	v_add_f32_e32 v135, v160, v135
	v_add_f32_e32 v128, v156, v135
	s_waitcnt lgkmcnt(1)
	v_mfma_f32_16x16x32_bf16 v[122:125], v[148:151], v[140:143], v[136:139]
	v_cvt_pk_bf16_f32 v136, v202, v203
	v_cvt_pk_bf16_f32 v137, v204, v205
	v_cvt_pk_bf16_f32 v138, v215, v217
	v_cvt_pk_bf16_f32 v139, v230, v184
	ds_read_b64_tr_b16 v[146:147], v231 offset:53760
	ds_read_b64_tr_b16 v[144:145], v231 offset:51200
	s_waitcnt lgkmcnt(2)
; __device__ __forceinline__ s16x4 vtr(const LAS unsigned char* p) { return __builtin_bit_cast(s16x4, __builtin_amdgcn_ds_read_tr16_b64_v4i16((LAS v4i16_t*)p)); }
; __device__ __forceinline__ unsigned cvtpk(float lo, float hi) { unsigned r; asm volatile("v_cvt_pk_bf16_f32 %0, %1, %2" : "=v"(r) : "v"(lo), "v"(hi)); return r; }
; __device__ __forceinline__ bf16x8 cat44(s16x4 lo, s16x4 hi) { return (bf16x8){lo[0], lo[1], lo[2], lo[3], hi[0], hi[1], hi[2], hi[3]}; }
; __device__ __forceinline__ void mixC_mfma(const bf16* P, const float* rpb  , bf16* MIX, LAS unsigned char* lds, int bid, int G, int tid) {
;     ...
;             for (int dt = 0; dt < 4; ++dt) {
;                 const s16x4 lo = vtr(vb + p * 64 * VROW + dt * 32), hi = vtr(vb + p * 64 * VROW + 16 * VROW + dt * 32);
;                 O[dt] = __builtin_amdgcn_mfma_f32_16x16x32_bf16(cat44(lo, hi), Pf, O[dt], 0, 0, 0);
;             }
;         }
;         const float inv = 1.0f / den;
;         bf16* op = MIX + qrow * DMIX + 768 + h * 64 + 4 * fq;
; #pragma unroll
;         for (int dt = 0; dt < 4; ++dt) { v2u w; w.x = cvtpk(O[dt][0] * inv, O[dt][1] * inv); w.y = cvtpk(O[dt][2] * inv, O[dt][3] * inv); *(v2u*)(op + 16 * dt) = w; }
	v_mfma_f32_16x16x32_bf16 v[114:117], v[152:155], v[140:143], v[114:117]
	ds_read_b64_tr_b16 v[142:143], v231 offset:53792
	ds_read_b64_tr_b16 v[140:141], v231 offset:51232
	ds_read_b64_tr_b16 v[148:149], v231 offset:51264
	ds_read_b64_tr_b16 v[152:153], v231 offset:51296
	ds_read_b64_tr_b16 v[150:151], v231 offset:53824
	ds_read_b64_tr_b16 v[154:155], v231 offset:53856
	v_add_f32_e32 v128, v133, v128
	v_add_f32_e32 v132, v157, v128
	v_sub_f32_e32 v128, v130, v134
	s_waitcnt lgkmcnt(6)
	v_mfma_f32_16x16x32_bf16 v[110:113], v[144:147], v[136:139], v[110:113]
	v_exp_f32_e32 v135, v128
	v_sub_f32_e32 v144, v129, v134
	v_cvt_pk_bf16_f32 v128, v185, v186
	s_waitcnt lgkmcnt(4)
	v_mfma_f32_16x16x32_bf16 v[118:121], v[140:143], v[136:139], v[118:121]
	v_cvt_pk_bf16_f32 v129, v172, v173
	v_cvt_pk_bf16_f32 v130, v174, v158
	v_cvt_pk_bf16_f32 v131, v159, v131
	ds_read_b64_tr_b16 v[142:143], v231 offset:64000
	ds_read_b64_tr_b16 v[140:141], v231 offset:61440
	v_exp_f32_e32 v158, v144
	v_sub_f32_e32 v127, v127, v134
	v_exp_f32_e32 v127, v127
	v_sub_f32_e32 v126, v126, v134
	s_waitcnt lgkmcnt(3)
	v_mfma_f32_16x16x32_bf16 v[122:125], v[148:151], v[136:139], v[122:125]
	v_exp_f32_e32 v126, v126
	v_add_f32_e32 v132, v135, v132
	s_lshl_b32 s4, s83, 6
	s_waitcnt lgkmcnt(2)
	v_mfma_f32_16x16x32_bf16 v[114:117], v[152:155], v[136:139], v[114:117]
	ds_read_b64_tr_b16 v[138:139], v231 offset:64032
	ds_read_b64_tr_b16 v[136:137], v231 offset:61472
	ds_read_b64_tr_b16 v[144:145], v231 offset:61504
	ds_read_b64_tr_b16 v[148:149], v231 offset:61536
	ds_read_b64_tr_b16 v[146:147], v231 offset:64064
	ds_read_b64_tr_b16 v[150:151], v231 offset:64096
	s_add_i32 s4, s4, s82
	v_mov_b32_e32 v217, v211
	s_waitcnt lgkmcnt(6)
	v_mfma_f32_16x16x32_bf16 v[110:113], v[140:143], v[128:131], v[110:113]
	v_add_f32_e32 v140, v158, v132
	v_cvt_pk_bf16_f32 v132, v160, v156
	v_cvt_pk_bf16_f32 v133, v133, v157
	v_cvt_pk_bf16_f32 v134, v135, v158
	v_cvt_pk_bf16_f32 v135, v127, v126
	v_add_f32_e32 v127, v127, v140
	s_waitcnt lgkmcnt(4)
	v_mfma_f32_16x16x32_bf16 v[118:121], v[136:139], v[128:131], v[118:121]
	v_add_u32_e32 v136, 0x11800, v231
	v_add_u32_e32 v138, 0x12200, v231
	v_add_f32_e32 v140, v126, v127
	s_waitcnt lgkmcnt(1)
	v_mfma_f32_16x16x32_bf16 v[122:125], v[144:147], v[128:131], v[122:125]
	ds_read_b64_tr_b16 v[136:137], v136
	ds_read_b64_tr_b16 v[138:139], v138
	v_add_u32_e32 v126, 0x11820, v231
	s_add_i32 s57, s57, s56
	s_waitcnt lgkmcnt(2)
	v_mfma_f32_16x16x32_bf16 v[114:117], v[148:151], v[128:131], v[114:117]
	ds_bpermute_b32 v130, v219, v140
	v_add_u32_e32 v128, 0x12220, v231
	v_add_u32_e32 v131, 0x11840, v231
	s_waitcnt lgkmcnt(1)
	v_mfma_f32_16x16x32_bf16 v[110:113], v[136:139], v[132:135], v[110:113]
	v_add_u32_e32 v138, 0x12240, v231
	s_waitcnt lgkmcnt(0)
	v_add_f32_e32 v130, v140, v130
	ds_read_b64_tr_b16 v[126:127], v126
	ds_read_b64_tr_b16 v[128:129], v128
	ds_read_b64_tr_b16 v[136:137], v131
	ds_read_b64_tr_b16 v[138:139], v138
	ds_bpermute_b32 v131, v220, v130
	s_waitcnt lgkmcnt(3)
	v_mfma_f32_16x16x32_bf16 v[118:121], v[126:129], v[132:135], v[118:121]
	v_add_u32_e32 v126, 0x11860, v231
	v_add_u32_e32 v128, 0x12260, v231
	s_waitcnt lgkmcnt(0)
	v_add_f32_e32 v130, v130, v131
	ds_read_b64_tr_b16 v[126:127], v126
	ds_read_b64_tr_b16 v[128:129], v128
	v_div_scale_f32 v131, s[0:1], v130, v130, 1.0
	v_mfma_f32_16x16x32_bf16 v[122:125], v[136:139], v[132:135], v[122:125]
	v_rcp_f32_e32 v136, v131
	v_or_b32_e32 v137, s4, v1
	s_waitcnt lgkmcnt(0)
	v_mfma_f32_16x16x32_bf16 v[114:117], v[126:129], v[132:135], v[114:117]
	v_fma_f32 v126, -v131, v136, 1.0
	v_fmac_f32_e32 v136, v126, v136
	v_div_scale_f32 v126, vcc, 1.0, v130, 1.0
	v_mul_f32_e32 v127, v126, v136
	v_fma_f32 v128, -v131, v127, v126
	v_fmac_f32_e32 v127, v128, v136
	v_fma_f32 v126, -v131, v127, v126
	v_div_fmas_f32 v126, v126, v136, v127
	v_div_fixup_f32 v128, v126, v130, 1.0
	v_mov_b64_e32 v[126:127], s[76:77]
	v_mad_i64_i32 v[126:127], s[0:1], v137, s81, v[126:127]
	v_mul_f32_e32 v110, v128, v110
	v_mul_f32_e32 v111, v128, v111
	v_lshl_add_u64 v[126:127], s[24:25], 1, v[126:127]
	v_cvt_pk_bf16_f32 v110, v110, v111
	v_mul_f32_e32 v111, v128, v112
	v_lshl_add_u64 v[126:127], v[126:127], 0, v[216:217]
	v_mul_f32_e32 v112, v128, v113
	v_cvt_pk_bf16_f32 v111, v111, v112
	v_mul_f32_e32 v112, v128, v118
	v_mul_f32_e32 v113, v128, v119
	v_cvt_pk_bf16_f32 v112, v112, v113
	v_mul_f32_e32 v113, v128, v120
	v_mul_f32_e32 v118, v128, v121
	v_cvt_pk_bf16_f32 v113, v113, v118
	v_bfe_u32 v250, v208, 4, 1
	v_mul_u32_u24_e32 v250, 24, v250
	v_mov_b32_e32 v251, 0
	v_lshl_add_u64 v[126:127], v[126:127], 0, v[250:251]
	v_permlane16_swap_b32 v110, v112
	v_permlane16_swap_b32 v111, v113
	global_store_dwordx4 v[126:127], v[110:113], off offset:1536
	v_mul_f32_e32 v118, v128, v122
	v_mul_f32_e32 v119, v128, v123
	v_cvt_pk_bf16_f32 v118, v118, v119
	v_mul_f32_e32 v119, v128, v124
	v_mul_f32_e32 v120, v128, v125
	v_cvt_pk_bf16_f32 v119, v119, v120
	v_mul_f32_e32 v120, v128, v114
	v_mul_f32_e32 v121, v128, v115
	v_cvt_pk_bf16_f32 v120, v120, v121
	v_mul_f32_e32 v121, v128, v116
	s_andn2_b64 vcc, exec, s[26:27]
	v_mul_f32_e32 v122, v128, v117
	v_cvt_pk_bf16_f32 v121, v121, v122
	s_nop 1
	v_permlane16_swap_b32 v118, v120
	v_permlane16_swap_b32 v119, v121
	global_store_dwordx4 v[126:127], v[118:121], off offset:1600
	s_cbranch_vccz .LBB0_1518
